# grid barrier: the 4th-from-last arriver of each XCD starts an early L2 write-back so the last arriver's release flush is nearly clean
# baseline (speedup 1.0000x reference)
; __device__ __forceinline__ unsigned xb_ld(unsigned* p)              { return __hip_atomic_load(p, __ATOMIC_RELAXED, __HIP_MEMORY_SCOPE_AGENT); }
; __device__ __forceinline__ unsigned xb_add(unsigned* p, unsigned v) { return __hip_atomic_fetch_add(p, v, __ATOMIC_RELAXED, __HIP_MEMORY_SCOPE_AGENT); }
; #define XB_SPIN(cond, bar) do { unsigned _sp = 0; while (cond) { __builtin_amdgcn_s_sleep(1); \
;     if ((++_sp & 255u) == 0u) { if (xb_ld(&(bar)[XB_TMO])) break; if (_sp > XB_SPIN_CAP) { atomicAdd(&(bar)[XB_TMO], 1u); break; } } } } while (0)
; __device__ __forceinline__ void xcd_barrier(const XcdBarrier& b) {
;     ...
;         unsigned nloc = b.st[0], nx = b.st[1];
;         if (nloc == 0u) { xcd_barrier_complete(bar, b.x, nloc, nx); b.st[0] = nloc; b.st[1] = nx; }
;         const unsigned old = xb_add(&bar[XB_XSUB(b.x)], 1u);
;         const unsigned gen = old / nloc;
;         if (old + 1u == (gen + 1u) * nloc) {
;             __builtin_amdgcn_fence(__ATOMIC_RELEASE, "agent");
;             asm volatile("s_waitcnt vmcnt(0)" ::: "memory");
;             const unsigned og = xb_add(&bar[XB_TOP], 1u);
;             const unsigned tg = og / nx;
;             if (og + 1u == (tg + 1u) * nx) xb_add(&bar[XB_TOPGEN], 1u);
;             else XB_SPIN(xb_ld(&bar[XB_TOPGEN]) == tg, bar);
.LBB0_36:
	s_or_b64 exec, exec, s[10:11]
	v_cvt_f32_u32_e32 v10, v4
	s_waitcnt vmcnt(0)
	v_readfirstlane_b32 s2, v5
	buffer_inv sc1
	v_sub_u32_e32 v5, 0, v4
	v_rcp_iflag_f32_e32 v10, v10
	v_add_u32_e32 v11, s2, v1
	v_mul_f32_e32 v10, 0x4f7ffffe, v10
	v_cvt_u32_f32_e32 v10, v10
	v_mul_lo_u32 v1, v5, v10
	v_mul_hi_u32 v1, v10, v1
	v_add_u32_e32 v1, v10, v1
	v_mul_hi_u32 v1, v11, v1
	v_mul_lo_u32 v5, v1, v4
	v_sub_u32_e32 v5, v11, v5
	v_add_u32_e32 v10, 1, v1
	v_cmp_ge_u32_e32 vcc, v5, v4
	s_nop 1
	v_cndmask_b32_e32 v1, v1, v10, vcc
	v_sub_u32_e32 v10, v5, v4
	v_cndmask_b32_e32 v5, v5, v10, vcc
	v_add_u32_e32 v10, 1, v1
	v_cmp_ge_u32_e32 vcc, v5, v4
	v_add_u32_e32 v5, 1, v11
	s_nop 0
	v_cndmask_b32_e32 v1, v1, v10, vcc
	v_mul_lo_u32 v10, v4, v1
	v_add_u32_e32 v4, v10, v4
	v_cmp_ne_u32_e32 vcc, v5, v4
	s_and_saveexec_b64 s[2:3], vcc
	s_xor_b64 s[8:9], exec, s[2:3]
	s_cbranch_execz .LBB0_50
	v_add_u32_e32 v10, 4, v5
	v_cmp_eq_u32_e32 vcc, v10, v4
	s_cbranch_vccz .Lpf_skip
	buffer_wbl2 sc1
.Lpf_skip:
	s_waitcnt lgkmcnt(0)
	global_load_dword v2, v252, s[6:7] offset:1024 sc1
	s_add_u32 s12, s6, 0x2400
	s_addc_u32 s13, s7, 0
	s_waitcnt vmcnt(0)
	v_cmp_eq_u32_e32 vcc, v2, v1
	s_and_saveexec_b64 s[10:11], vcc
	s_cbranch_execz .LBB0_49
	s_mov_b32 s2, 1
	s_mov_b64 s[14:15], 0
	s_branch .LBB0_40
